# gatenorm row loop: row-invariant norm weights loaded once before the loop; the two weight-only load batches (each with a full wait per row) become register moves
# baseline (speedup 1.0000x reference)
.LBB0_1137:
	s_andn2_b64 vcc, exec, s[0:1]
	s_cbranch_vccnz .LBB0_1205
	v_readlane_b32 s3, v246, 0
	s_cmp_gt_i32 s3, 31
	s_mov_b64 s[0:1], -1
	v_mov_b32_e32 v1, v180
	s_lshl_b32 s0, s3, 3
	s_movk_i32 s69, 0x3ff
	s_cmp_gt_u32 s3, 127
	s_cselect_b32 s64, 0x400, 0
	s_cselect_b32 s65, 0, 0xfffffc00
	s_cselect_b32 s69, 0x1bff, s69
	s_add_i32 s1, s0, s64
	v_ashrrev_i32_e32 v2, 6, v1
	v_add_u32_e32 v0, s1, v2
	v_cmp_gt_i32_e32 vcc, s87, v0
	s_and_saveexec_b64 s[8:9], vcc
	s_mov_b32 s15, 0xe900000
	s_mov_b32 s20, 0x10d03000
	s_mov_b32 s34, 0x358637bd
	s_mov_b32 s36, 0x3b800000
	s_brev_b32 s40, 60
	s_cbranch_execz .LBB0_1142
	v_and_b32_e32 v4, 64, v182
	v_xor_b32_e32 v3, 1, v182
	v_add_u32_e32 v4, 64, v4
	v_cmp_lt_i32_e32 vcc, v3, v4
	s_lshl_b64 s[6:7], s[24:25], 2
	s_add_u32 s6, s2, s6
	v_cndmask_b32_e32 v3, v182, v3, vcc
	v_lshlrev_b32_e32 v88, 2, v3
	v_xor_b32_e32 v3, 2, v182
	v_cmp_lt_i32_e32 vcc, v3, v4
	s_addc_u32 s7, s4, s7
	v_add_u32_e32 v2, s0, v2
	v_cndmask_b32_e32 v3, v182, v3, vcc
	v_lshlrev_b32_e32 v89, 2, v3
	v_xor_b32_e32 v3, 4, v182
	v_cmp_lt_i32_e32 vcc, v3, v4
	v_add_u32_e32 v93, s65, v2
	s_mov_b64 s[12:13], 0
	v_cndmask_b32_e32 v3, v182, v3, vcc
	v_lshlrev_b32_e32 v90, 2, v3
	v_xor_b32_e32 v3, 8, v182
	v_cmp_lt_i32_e32 vcc, v3, v4
	s_nop 1
	v_cndmask_b32_e32 v3, v182, v3, vcc
	v_lshlrev_b32_e32 v91, 2, v3
	v_xor_b32_e32 v3, 16, v182
	v_cmp_lt_i32_e32 vcc, v3, v4
	s_nop 1
	v_cndmask_b32_e32 v3, v182, v3, vcc
	v_lshlrev_b32_e32 v92, 2, v3
	v_lshlrev_b32_e32 v3, 5, v1
	v_and_b32_e32 v144, 0x1e0, v3
	v_lshl_add_u64 v[8:9], s[6:7], 0, v[144:145]
	s_lshl_b64 s[6:7], s[38:39], 2
	s_add_u32 s4, s5, s6
	s_addc_u32 s5, s14, s7
	v_and_b32_e32 v144, 0x3e0, v3
	v_and_b32_e32 v1, 63, v1
	v_lshl_add_u64 v[10:11], s[4:5], 0, v[144:145]
	v_lshlrev_b32_e32 v144, 4, v1
	v_ashrrev_i32_e32 v1, 31, v0
	v_mov_b64_e32 v[2:3], s[26:27]
	v_mad_i64_i32 v[12:13], s[0:1], v0, s86, v[2:3]
	v_lshlrev_b64 v[0:1], 12, v[0:1]
	v_lshl_add_u64 v[14:15], s[26:27], 0, v[0:1]
	flat_load_dwordx4 v[190:193], v[8:9]
	flat_load_dwordx4 v[194:197], v[8:9] offset:16
	flat_load_dwordx4 v[198:201], v[10:11]
	flat_load_dwordx4 v[202:205], v[10:11] offset:16
	s_waitcnt vmcnt(0) lgkmcnt(0)
.LBB0_1141:
	v_lshl_add_u64 v[20:21], v[14:15], 0, v[144:145]
	v_add_co_u32_e32 v16, vcc, 0xc500000, v20
	v_lshl_add_u64 v[18:19], v[12:13], 0, v[144:145]
	s_nop 0
	v_addc_co_u32_e32 v17, vcc, 0, v21, vcc
	flat_load_dwordx4 v[38:41], v[16:17]
	v_add_co_u32_e32 v24, vcc, 0x10d01000, v18
	v_add_u32_e32 v93, 0x400, v93
	s_nop 0
	v_addc_co_u32_e32 v25, vcc, 0, v19, vcc
	flat_load_dwordx4 v[42:45], v[24:25] offset:2080
	flat_load_dwordx4 v[4:7], v[8:9]
	flat_load_dwordx4 v[0:3], v[8:9] offset:16
	flat_load_dwordx4 v[82:85], v[16:17] offset:1024
	flat_load_dwordx4 v[94:97], v[24:25] offset:3104
	s_waitcnt vmcnt(0) lgkmcnt(0)
	v_and_b32_e32 v23, 0xffff0000, v41
	v_lshlrev_b32_e32 v27, 16, v41
	v_mov_b32_e32 v28, v23
	v_mov_b32_e32 v29, v27
	v_lshlrev_b32_e32 v26, 16, v45
	v_pk_mul_f32 v[86:87], v[28:29], v[28:29]
	v_mul_f32_e32 v28, 0xbfb8aa3b, v26
	v_exp_f32_e32 v28, v28
	v_and_b32_e32 v32, 0xffff0000, v44
	v_and_b32_e32 v33, 0xffff0000, v40
	v_lshlrev_b32_e32 v41, 16, v40
	v_add_f32_e32 v28, 1.0, v28
	v_rcp_f32_e32 v30, v28
	v_mul_f32_e32 v28, 0xbfb8aa3b, v32
	v_exp_f32_e32 v28, v28
	v_lshlrev_b32_e32 v40, 16, v44
	v_mov_b32_e32 v29, v41
	v_and_b32_e32 v48, 0xffff0000, v43
	v_add_f32_e32 v28, 1.0, v28
	v_rcp_f32_e32 v36, v28
	v_mov_b32_e32 v28, v33
	v_pk_mul_f32 v[98:99], v[28:29], v[28:29]
	v_mul_f32_e32 v28, 0xbfb8aa3b, v40
	v_exp_f32_e32 v28, v28
	v_and_b32_e32 v49, 0xffff0000, v39
	v_lshlrev_b32_e32 v57, 16, v39
	v_lshlrev_b32_e32 v56, 16, v43
	v_add_f32_e32 v28, 1.0, v28
	v_rcp_f32_e32 v46, v28
	v_mul_f32_e32 v28, 0xbfb8aa3b, v48
	v_exp_f32_e32 v28, v28
	v_mov_b32_e32 v29, v57
	v_and_b32_e32 v70, 0xffff0000, v42
	v_lshlrev_b32_e32 v78, 16, v42
	v_add_f32_e32 v28, 1.0, v28
	v_rcp_f32_e32 v52, v28
	v_mov_b32_e32 v28, v49
	v_pk_mul_f32 v[100:101], v[28:29], v[28:29]
	v_mul_f32_e32 v28, 0xbfb8aa3b, v56
	v_exp_f32_e32 v28, v28
	v_and_b32_e32 v22, 0xffff0000, v45
	v_and_b32_e32 v25, 0xffff0000, v85
	v_lshlrev_b32_e32 v29, 16, v85
	v_add_f32_e32 v28, 1.0, v28
	v_rcp_f32_e32 v68, v28
	v_mul_f32_e32 v28, 0xbfb8aa3b, v70
	v_exp_f32_e32 v28, v28
	v_and_b32_e32 v71, 0xffff0000, v38
	v_lshlrev_b32_e32 v79, 16, v38
	v_mov_b32_e32 v34, v25
	v_add_f32_e32 v28, 1.0, v28
	v_rcp_f32_e32 v74, v28
	v_mul_f32_e32 v28, 0xbfb8aa3b, v78
	v_exp_f32_e32 v28, v28
	v_mov_b32_e32 v35, v29
	v_and_b32_e32 v38, 0xffff0000, v96
	v_pk_mul_f32 v[102:103], v[34:35], v[34:35]
	v_add_f32_e32 v28, 1.0, v28
	v_rcp_f32_e32 v60, v28
	v_mul_f32_e32 v28, 0xbfb8aa3b, v22
	v_exp_f32_e32 v28, v28
	v_and_b32_e32 v55, 0xffff0000, v83
	v_lshlrev_b32_e32 v67, 16, v83
	v_and_b32_e32 v77, 0xffff0000, v82
	v_add_f32_e32 v28, 1.0, v28
	v_rcp_f32_e32 v64, v28
	v_lshlrev_b32_e32 v28, 16, v97
	v_mul_f32_e32 v31, 0xbfb8aa3b, v28
	v_exp_f32_e32 v31, v31
	v_and_b32_e32 v54, 0xffff0000, v95
	v_lshlrev_b32_e32 v66, 16, v95
	v_mov_b32_e32 v62, v55
	v_add_f32_e32 v31, 1.0, v31
	v_rcp_f32_e32 v34, v31
	v_mul_f32_e32 v31, 0xbfb8aa3b, v38
	v_exp_f32_e32 v31, v31
	v_mov_b32_e32 v63, v67
	v_and_b32_e32 v76, 0xffff0000, v94
	v_lshlrev_b32_e32 v83, 16, v82
	v_lshlrev_b32_e32 v82, 16, v94
	v_mov_b32_e32 v94, v77
	v_mov_b32_e32 v95, v71
	v_and_b32_e32 v24, 0xffff0000, v97
	v_and_b32_e32 v39, 0xffff0000, v84
	v_lshlrev_b32_e32 v45, 16, v84
	v_lshlrev_b32_e32 v44, 16, v96
	v_pk_mul_f32 v[96:97], v[62:63], v[62:63]
	v_pk_mul_f32 v[94:95], v[94:95], v[94:95]
	v_mov_b32_e32 v104, v83
	v_mov_b32_e32 v105, v79
	v_mov_b32_e32 v50, v39
	v_mov_b32_e32 v51, v45
	v_pk_fma_f32 v[94:95], v[104:105], v[104:105], v[94:95]
	v_mov_b32_e32 v104, v97
	v_mov_b32_e32 v105, v101
	v_add_f32_e32 v31, 1.0, v31
	v_pk_mul_f32 v[84:85], v[50:51], v[50:51]
	v_pk_add_f32 v[94:95], v[104:105], v[94:95]
	v_mov_b32_e32 v97, v100
	v_rcp_f32_e32 v42, v31
	v_mul_f32_e32 v31, 0xbfb8aa3b, v44
	v_pk_add_f32 v[94:95], v[96:97], v[94:95]
	v_mov_b32_e32 v96, v85
	v_mov_b32_e32 v97, v99
	v_exp_f32_e32 v31, v31
	v_pk_add_f32 v[94:95], v[96:97], v[94:95]
	v_mov_b32_e32 v85, v98
	v_pk_add_f32 v[84:85], v[84:85], v[94:95]
	v_mov_b32_e32 v94, v103
	v_mov_b32_e32 v95, v87
	v_pk_add_f32 v[84:85], v[94:95], v[84:85]
	v_mov_b32_e32 v103, v86
	v_pk_add_f32 v[84:85], v[102:103], v[84:85]
	v_add_f32_e32 v31, 1.0, v31
	ds_bpermute_b32 v87, v88, v85
	ds_bpermute_b32 v86, v88, v84
	v_rcp_f32_e32 v50, v31
	v_mul_f32_e32 v31, 0xbfb8aa3b, v54
	v_exp_f32_e32 v31, v31
	s_waitcnt lgkmcnt(0)
	v_pk_add_f32 v[84:85], v[84:85], v[86:87]
	ds_bpermute_b32 v87, v89, v85
	v_add_f32_e32 v31, 1.0, v31
	ds_bpermute_b32 v86, v89, v84
	v_rcp_f32_e32 v58, v31
	v_mul_f32_e32 v31, 0xbfb8aa3b, v66
	v_exp_f32_e32 v31, v31
	s_waitcnt lgkmcnt(0)
	v_pk_add_f32 v[84:85], v[84:85], v[86:87]
	ds_bpermute_b32 v87, v90, v85
	v_add_f32_e32 v31, 1.0, v31
	ds_bpermute_b32 v86, v90, v84
	v_rcp_f32_e32 v72, v31
	v_mul_f32_e32 v31, 0xbfb8aa3b, v76
	v_exp_f32_e32 v31, v31
	s_waitcnt lgkmcnt(0)
	v_pk_add_f32 v[84:85], v[84:85], v[86:87]
	ds_bpermute_b32 v87, v91, v85
	v_add_f32_e32 v31, 1.0, v31
	ds_bpermute_b32 v86, v91, v84
	v_rcp_f32_e32 v80, v31
	v_mul_f32_e32 v31, 0xbfb8aa3b, v82
	v_exp_f32_e32 v31, v31
	s_waitcnt lgkmcnt(0)
	v_pk_add_f32 v[84:85], v[84:85], v[86:87]
	v_mov_b64_e32 v[86:87], s[34:35]
	v_add_f32_e32 v31, 1.0, v31
	v_pk_fma_f32 v[84:85], v[84:85], s[40:41], v[86:87] op_sel_hi:[1,0,0]
	v_rcp_f32_e32 v62, v31
	v_mul_f32_e32 v31, 0x4b800000, v85
	v_cmp_gt_f32_e64 s[0:1], s80, v85
	v_cmp_gt_f32_e32 vcc, s80, v84
	s_nop 0
	v_cndmask_b32_e64 v31, v85, v31, s[0:1]
	v_rsq_f32_e32 v31, v31
	s_nop 0
	v_mul_f32_e32 v35, 0x45800000, v31
	v_cndmask_b32_e64 v61, v31, v35, s[0:1]
	v_pk_mul_f32 v[78:79], v[60:61], v[78:79]
	v_mov_b32_e32 v75, v61
	v_mul_f32_e32 v4, v4, v79
	v_pk_mul_f32 v[70:71], v[74:75], v[70:71]
	v_mul_f32_e32 v35, v78, v4
	v_mul_f32_e32 v4, v5, v71
	v_mov_b32_e32 v69, v61
	v_mul_f32_e32 v43, v70, v4
	v_pk_mul_f32 v[4:5], v[68:69], v[56:57]
	v_mov_b32_e32 v53, v61
	v_mul_f32_e32 v5, v6, v5
	v_mul_f32_e32 v6, v4, v5
	v_pk_mul_f32 v[4:5], v[52:53], v[48:49]
	v_mov_b32_e32 v47, v61
	v_mul_f32_e32 v5, v7, v5
	v_mul_f32_e32 v7, v4, v5
	v_pk_mul_f32 v[4:5], v[46:47], v[40:41]
	v_mov_b32_e32 v37, v61
	v_mul_f32_e32 v0, v0, v5
	v_mul_f32_e32 v40, v4, v0
	v_pk_mul_f32 v[4:5], v[36:37], v[32:33]
	v_mov_b32_e32 v31, v61
	v_mul_f32_e32 v0, v1, v5
	v_mul_f32_e32 v4, v4, v0
	v_pk_mul_f32 v[0:1], v[30:31], v[26:27]
	v_mov_b32_e32 v65, v61
	v_mul_f32_e32 v1, v2, v1
	v_mul_f32_e32 v5, v0, v1
	v_pk_mul_f32 v[0:1], v[64:65], v[22:23]
	v_add_u32_e32 v2, 0x8000, v35
	v_mul_f32_e32 v1, v3, v1
	v_mul_f32_e32 v0, v0, v1
	v_add_u32_e32 v1, 0x8000, v43
	v_perm_b32 v2, v1, v2, s81
	v_add_u32_e32 v1, 0x8000, v7
	v_add_u32_e32 v3, 0x8000, v6
	v_perm_b32 v3, v1, v3, s81
	v_add_u32_e32 v1, 0x8000, v4
	v_add_u32_e32 v4, 0x8000, v40
	v_perm_b32 v4, v1, v4, s81
	v_add_u32_e32 v0, 0x8000, v0
	v_add_u32_e32 v1, 0x8000, v5
	v_perm_b32 v5, v0, v1, s81
	v_add_co_u32_e64 v0, s[0:1], s15, v20
	v_mul_f32_e32 v6, 0x4b800000, v84
	s_nop 0
	v_addc_co_u32_e64 v1, s[0:1], 0, v21, s[0:1]
	flat_store_dwordx4 v[0:1], v[2:5]
	s_nop 1
	v_mov_b32_e32 v2, v194
	v_mov_b32_e32 v3, v195
	v_mov_b32_e32 v4, v196
	v_mov_b32_e32 v5, v197
	s_nop 0
	v_mov_b32_e32 v20, v190
	v_mov_b32_e32 v21, v191
	v_mov_b32_e32 v22, v192
	v_mov_b32_e32 v23, v193
	v_cndmask_b32_e32 v6, v84, v6, vcc
	v_rsq_f32_e32 v6, v6
	s_nop 0
	v_mul_f32_e32 v7, 0x45800000, v6
	v_cndmask_b32_e32 v63, v6, v7, vcc
	v_pk_mul_f32 v[6:7], v[62:63], v[82:83]
	v_mov_b32_e32 v81, v63
	v_mov_b32_e32 v73, v63
	v_mov_b32_e32 v59, v63
	v_mov_b32_e32 v51, v63
	v_mov_b32_e32 v43, v63
	v_mov_b32_e32 v35, v63
	v_mul_f32_e32 v7, v20, v7
	v_mul_f32_e32 v20, v6, v7
	v_pk_mul_f32 v[6:7], v[80:81], v[76:77]
	s_nop 0
	v_mul_f32_e32 v7, v21, v7
	v_mul_f32_e32 v21, v6, v7
	v_pk_mul_f32 v[6:7], v[72:73], v[66:67]
	s_nop 0
	v_mul_f32_e32 v7, v22, v7
	v_mul_f32_e32 v22, v6, v7
	v_pk_mul_f32 v[6:7], v[58:59], v[54:55]
	s_nop 0
	v_mul_f32_e32 v7, v23, v7
	v_mul_f32_e32 v23, v6, v7
	v_pk_mul_f32 v[6:7], v[50:51], v[44:45]
	s_nop 0
	v_mul_f32_e32 v2, v2, v7
	v_mul_f32_e32 v26, v6, v2
	v_pk_mul_f32 v[6:7], v[42:43], v[38:39]
	s_nop 0
	v_mul_f32_e32 v2, v3, v7
	v_mul_f32_e32 v6, v6, v2
	v_pk_mul_f32 v[2:3], v[34:35], v[28:29]
	s_nop 0
	v_mul_f32_e32 v3, v4, v3
	v_mul_f32_e32 v7, v2, v3
	v_mul_f32_e32 v2, 0xbfb8aa3b, v24
	v_exp_f32_e32 v2, v2
	v_add_u32_e32 v4, 0x8000, v22
	v_add_f32_e32 v2, 1.0, v2
	v_rcp_f32_e32 v62, v2
	s_nop 0
	v_pk_mul_f32 v[2:3], v[62:63], v[24:25]
	s_nop 0
	v_mul_f32_e32 v3, v5, v3
	v_mul_f32_e32 v5, v2, v3
	v_add_u32_e32 v2, 0x8000, v21
	v_add_u32_e32 v3, 0x8000, v20
	v_perm_b32 v2, v2, v3, s81
	v_add_u32_e32 v3, 0x8000, v23
	v_perm_b32 v3, v3, v4, s81
	v_add_u32_e32 v4, 0x8000, v6
	v_add_u32_e32 v6, 0x8000, v26
	v_perm_b32 v4, v4, v6, s81
	v_add_u32_e32 v5, 0x8000, v5
	v_add_u32_e32 v6, 0x8000, v7
	v_perm_b32 v5, v5, v6, s81
	v_add_co_u32_e32 v6, vcc, s20, v18
	flat_store_dwordx4 v[0:1], v[2:5] offset:1024
	flat_load_dwordx4 v[2:5], v[16:17] offset:2048
	v_addc_co_u32_e32 v7, vcc, 0, v19, vcc
	flat_load_dwordx4 v[18:21], v[6:7] offset:64
	flat_load_dwordx4 v[22:25], v[10:11]
	flat_load_dwordx4 v[26:29], v[10:11] offset:16
	s_waitcnt vmcnt(0) lgkmcnt(0)
	v_and_b32_e32 v31, 0xffff0000, v5
	v_lshlrev_b32_e32 v32, 16, v21
	v_lshlrev_b32_e32 v33, 16, v5
	v_mul_f32_e32 v5, 0xbfb8aa3b, v32
	v_exp_f32_e32 v5, v5
	v_and_b32_e32 v38, 0xffff0000, v20
	v_and_b32_e32 v30, 0xffff0000, v21
	v_and_b32_e32 v39, 0xffff0000, v4
	v_add_f32_e32 v5, 1.0, v5
	v_rcp_f32_e32 v36, v5
	v_mul_f32_e32 v5, 0xbfb8aa3b, v38
	v_exp_f32_e32 v5, v5
	v_lshlrev_b32_e32 v21, 16, v4
	v_lshlrev_b32_e32 v20, 16, v20
	v_mov_b32_e32 v4, v39
	v_add_f32_e32 v5, 1.0, v5
	v_rcp_f32_e32 v40, v5
	v_mov_b32_e32 v5, v21
	v_pk_mul_f32 v[42:43], v[4:5], v[4:5]
	v_mul_f32_e32 v4, 0xbfb8aa3b, v20
	v_lshlrev_b32_e32 v50, 16, v19
	v_lshlrev_b32_e32 v60, 16, v18
	v_exp_f32_e32 v4, v4
	v_and_b32_e32 v47, 0xffff0000, v3
	v_lshlrev_b32_e32 v51, 16, v3
	v_mul_f32_e32 v3, 0xbfb8aa3b, v50
	v_and_b32_e32 v57, 0xffff0000, v2
	v_lshlrev_b32_e32 v61, 16, v2
	v_mul_f32_e32 v2, 0xbfb8aa3b, v60
	v_exp_f32_e32 v3, v3
	v_exp_f32_e32 v2, v2
	v_add_f32_e32 v4, 1.0, v4
	v_and_b32_e32 v46, 0xffff0000, v19
	v_rcp_f32_e32 v44, v4
	v_mul_f32_e32 v4, 0xbfb8aa3b, v46
	v_add_f32_e32 v3, 1.0, v3
	v_and_b32_e32 v56, 0xffff0000, v18
	v_add_f32_e32 v2, 1.0, v2
	v_exp_f32_e32 v4, v4
	v_rcp_f32_e32 v54, v3
	v_mul_f32_e32 v3, 0xbfb8aa3b, v56
	v_rcp_f32_e32 v62, v2
	v_mul_f32_e32 v2, 0xbfb8aa3b, v30
	v_exp_f32_e32 v3, v3
	v_exp_f32_e32 v2, v2
	v_add_f32_e32 v4, 1.0, v4
	v_rcp_f32_e32 v48, v4
	v_mov_b32_e32 v4, v47
	v_mov_b32_e32 v5, v51
	v_add_f32_e32 v3, 1.0, v3
	v_add_f32_e32 v2, 1.0, v2
	v_pk_mul_f32 v[52:53], v[4:5], v[4:5]
	v_rcp_f32_e32 v58, v3
	v_rcp_f32_e32 v64, v2
	flat_load_dwordx4 v[2:5], v[16:17] offset:3072
	s_nop 0
	flat_load_dwordx4 v[16:19], v[6:7] offset:1088
	v_mov_b32_e32 v34, v31
	v_mov_b32_e32 v35, v33
	v_pk_mul_f32 v[34:35], v[34:35], v[34:35]
	s_waitcnt vmcnt(0) lgkmcnt(0)
	v_and_b32_e32 v81, 0xffff0000, v3
	v_lshlrev_b32_e32 v76, 16, v18
	v_lshlrev_b32_e32 v84, 16, v17
	v_and_b32_e32 v72, 0xffff0000, v18
	v_mul_f32_e32 v18, 0xbfb8aa3b, v76
	v_lshlrev_b32_e32 v85, 16, v3
	v_mul_f32_e32 v3, 0xbfb8aa3b, v84
	v_lshlrev_b32_e32 v66, 16, v19
	v_exp_f32_e32 v18, v18
	v_exp_f32_e32 v3, v3
	v_and_b32_e32 v7, 0xffff0000, v5
	v_lshlrev_b32_e32 v67, 16, v5
	v_mul_f32_e32 v5, 0xbfb8aa3b, v66
	v_exp_f32_e32 v5, v5
	v_add_f32_e32 v18, 1.0, v18
	v_and_b32_e32 v80, 0xffff0000, v17
	v_add_f32_e32 v3, 1.0, v3
	v_and_b32_e32 v96, 0xffff0000, v16
	v_lshlrev_b32_e32 v100, 16, v16
	v_rcp_f32_e32 v78, v18
	v_mul_f32_e32 v18, 0xbfb8aa3b, v80
	v_rcp_f32_e32 v94, v3
	v_and_b32_e32 v97, 0xffff0000, v2
	v_mul_f32_e32 v3, 0xbfb8aa3b, v96
	v_lshlrev_b32_e32 v101, 16, v2
	v_mul_f32_e32 v2, 0xbfb8aa3b, v100
	v_add_f32_e32 v5, 1.0, v5
	v_exp_f32_e32 v18, v18
	v_exp_f32_e32 v3, v3
	v_exp_f32_e32 v2, v2
	v_rcp_f32_e32 v70, v5
	v_mul_f32_e32 v5, 0xbfb8aa3b, v72
	v_exp_f32_e32 v5, v5
	v_add_f32_e32 v18, 1.0, v18
	v_add_f32_e32 v3, 1.0, v3
	v_add_f32_e32 v2, 1.0, v2
	v_and_b32_e32 v6, 0xffff0000, v19
	v_rcp_f32_e32 v82, v18
	v_mov_b32_e32 v18, v81
	v_mov_b32_e32 v19, v85
	v_rcp_f32_e32 v98, v3
	v_rcp_f32_e32 v102, v2
	v_mov_b32_e32 v2, v97
	v_mov_b32_e32 v3, v57
	v_and_b32_e32 v73, 0xffff0000, v4
	v_add_f32_e32 v5, 1.0, v5
	v_lshlrev_b32_e32 v77, 16, v4
	v_pk_mul_f32 v[18:19], v[18:19], v[18:19]
	v_pk_mul_f32 v[2:3], v[2:3], v[2:3]
	v_mov_b32_e32 v16, v101
	v_mov_b32_e32 v17, v61
	v_rcp_f32_e32 v74, v5
	v_mov_b32_e32 v4, v73
	v_mov_b32_e32 v5, v77
	v_pk_fma_f32 v[2:3], v[16:17], v[16:17], v[2:3]
	v_mov_b32_e32 v16, v19
	v_mov_b32_e32 v17, v53
	v_pk_mul_f32 v[4:5], v[4:5], v[4:5]
	v_pk_add_f32 v[2:3], v[16:17], v[2:3]
	v_mov_b32_e32 v19, v52
	v_mov_b32_e32 v68, v7
	v_mov_b32_e32 v69, v67
	v_pk_add_f32 v[2:3], v[18:19], v[2:3]
	v_mov_b32_e32 v16, v5
	v_mov_b32_e32 v17, v43
	v_pk_mul_f32 v[68:69], v[68:69], v[68:69]
	v_pk_add_f32 v[2:3], v[16:17], v[2:3]
	v_mov_b32_e32 v5, v42
	v_pk_add_f32 v[2:3], v[4:5], v[2:3]
	v_mov_b32_e32 v4, v69
	v_mov_b32_e32 v5, v35
	v_pk_add_f32 v[2:3], v[4:5], v[2:3]
	v_mov_b32_e32 v69, v34
	v_pk_add_f32 v[2:3], v[68:69], v[2:3]
	ds_bpermute_b32 v5, v88, v3
	ds_bpermute_b32 v4, v88, v2
	s_waitcnt lgkmcnt(0)
	v_pk_add_f32 v[2:3], v[2:3], v[4:5]
	ds_bpermute_b32 v5, v89, v3
	ds_bpermute_b32 v4, v89, v2
	s_waitcnt lgkmcnt(0)
	v_pk_add_f32 v[2:3], v[2:3], v[4:5]
	ds_bpermute_b32 v5, v90, v3
	ds_bpermute_b32 v4, v90, v2
	s_waitcnt lgkmcnt(0)
	v_pk_add_f32 v[2:3], v[2:3], v[4:5]
	ds_bpermute_b32 v5, v91, v3
	ds_bpermute_b32 v4, v91, v2
	s_waitcnt lgkmcnt(0)
	v_pk_add_f32 v[2:3], v[2:3], v[4:5]
	ds_bpermute_b32 v5, v92, v3
	ds_bpermute_b32 v4, v92, v2
	s_waitcnt lgkmcnt(0)
	v_pk_add_f32 v[2:3], v[2:3], v[4:5]
	s_nop 0
	v_pk_fma_f32 v[34:35], v[2:3], s[36:37], v[86:87] op_sel_hi:[1,0,0]
	s_nop 0
	v_mul_f32_e32 v2, 0x4b800000, v35
	v_cmp_gt_f32_e64 s[0:1], s80, v35
	v_cmp_gt_f32_e32 vcc, s80, v34
	s_nop 0
	v_cndmask_b32_e64 v2, v35, v2, s[0:1]
	v_rsq_f32_e32 v2, v2
	s_nop 0
	v_mul_f32_e32 v3, 0x45800000, v2
	v_cndmask_b32_e64 v63, v2, v3, s[0:1]
	v_pk_mul_f32 v[2:3], v[62:63], v[60:61]
	v_mov_b32_e32 v59, v63
	v_mul_f32_e32 v3, v22, v3
	v_mul_f32_e32 v4, v2, v3
	v_pk_mul_f32 v[2:3], v[58:59], v[56:57]
	v_mov_b32_e32 v55, v63
	v_mul_f32_e32 v3, v23, v3
	v_mul_f32_e32 v5, v2, v3
	v_pk_mul_f32 v[2:3], v[54:55], v[50:51]
	v_mov_b32_e32 v49, v63
	v_mul_f32_e32 v3, v24, v3
	v_mul_f32_e32 v16, v2, v3
	v_pk_mul_f32 v[2:3], v[48:49], v[46:47]
	v_mov_b32_e32 v45, v63
	v_mul_f32_e32 v3, v25, v3
	v_mul_f32_e32 v17, v2, v3
	v_pk_mul_f32 v[2:3], v[44:45], v[20:21]
	v_mov_b32_e32 v41, v63
	v_mul_f32_e32 v3, v26, v3
	v_mul_f32_e32 v18, v2, v3
	v_pk_mul_f32 v[2:3], v[40:41], v[38:39]
	v_mov_b32_e32 v37, v63
	v_mul_f32_e32 v3, v27, v3
	v_mul_f32_e32 v19, v2, v3
	v_pk_mul_f32 v[2:3], v[36:37], v[32:33]
	v_mov_b32_e32 v65, v63
	v_mul_f32_e32 v3, v28, v3
	v_mul_f32_e32 v20, v2, v3
	v_pk_mul_f32 v[2:3], v[64:65], v[30:31]
	s_mov_b64 s[0:1], 0xe80000
	v_mul_f32_e32 v3, v29, v3
	v_mul_f32_e32 v21, v2, v3
	v_add_u32_e32 v2, 0x8000, v5
	v_add_u32_e32 v3, 0x8000, v4
	v_perm_b32 v2, v2, v3, s81
	v_add_u32_e32 v3, 0x8000, v17
	v_add_u32_e32 v4, 0x8000, v16
	v_perm_b32 v3, v3, v4, s81
	v_add_u32_e32 v4, 0x8000, v19
	v_add_u32_e32 v5, 0x8000, v18
	v_perm_b32 v4, v4, v5, s81
	v_add_u32_e32 v5, 0x8000, v21
	v_add_u32_e32 v16, 0x8000, v20
	v_perm_b32 v5, v5, v16, s81
	flat_store_dwordx4 v[0:1], v[2:5] offset:2048
	s_nop 1
	v_mov_b32_e32 v2, v198
	v_mov_b32_e32 v3, v199
	v_mov_b32_e32 v4, v200
	v_mov_b32_e32 v5, v201
	s_nop 0
	v_mov_b32_e32 v16, v202
	v_mov_b32_e32 v17, v203
	v_mov_b32_e32 v18, v204
	v_mov_b32_e32 v19, v205
	v_mul_f32_e32 v20, 0x4b800000, v34
	v_cndmask_b32_e32 v20, v34, v20, vcc
	v_rsq_f32_e32 v20, v20
	v_lshl_add_u64 v[12:13], v[12:13], 0, s[0:1]
	s_mov_b64 s[0:1], 0x400000
	v_lshl_add_u64 v[14:15], v[14:15], 0, s[0:1]
	v_mul_f32_e32 v21, 0x45800000, v20
	v_cndmask_b32_e32 v103, v20, v21, vcc
	v_pk_mul_f32 v[20:21], v[102:103], v[100:101]
	v_mov_b32_e32 v99, v103
	v_mov_b32_e32 v95, v103
	v_mov_b32_e32 v83, v103
	v_mov_b32_e32 v79, v103
	v_mov_b32_e32 v75, v103
	v_mov_b32_e32 v71, v103
	s_mov_b32 s0, s69
	v_cmp_lt_i32_e32 vcc, s0, v93
	s_or_b64 s[12:13], vcc, s[12:13]
	v_mul_f32_e32 v2, v2, v21
	v_mul_f32_e32 v22, v20, v2
	v_pk_mul_f32 v[20:21], v[98:99], v[96:97]
	s_nop 0
	v_mul_f32_e32 v2, v3, v21
	v_mul_f32_e32 v20, v20, v2
	v_pk_mul_f32 v[2:3], v[94:95], v[84:85]
	s_nop 0
	v_mul_f32_e32 v3, v4, v3
	v_mul_f32_e32 v4, v2, v3
	v_pk_mul_f32 v[2:3], v[82:83], v[80:81]
	v_add_u32_e32 v4, 0x8000, v4
	v_mul_f32_e32 v3, v5, v3
	v_mul_f32_e32 v5, v2, v3
	v_pk_mul_f32 v[2:3], v[78:79], v[76:77]
	s_nop 0
	v_mul_f32_e32 v3, v16, v3
	v_mul_f32_e32 v16, v2, v3
	v_pk_mul_f32 v[2:3], v[74:75], v[72:73]
	s_nop 0
	v_mul_f32_e32 v3, v17, v3
	v_mul_f32_e32 v17, v2, v3
	v_pk_mul_f32 v[2:3], v[70:71], v[66:67]
	s_nop 0
	v_mul_f32_e32 v3, v18, v3
	v_mul_f32_e32 v18, v2, v3
	v_mul_f32_e32 v2, 0xbfb8aa3b, v6
	v_exp_f32_e32 v2, v2
	s_nop 0
	v_add_f32_e32 v2, 1.0, v2
	v_rcp_f32_e32 v102, v2
	s_nop 0
	v_pk_mul_f32 v[2:3], v[102:103], v[6:7]
	s_nop 0
	v_mul_f32_e32 v3, v19, v3
	v_mul_f32_e32 v6, v2, v3
	v_add_u32_e32 v2, 0x8000, v20
	v_add_u32_e32 v3, 0x8000, v22
	v_perm_b32 v2, v2, v3, s81
	v_add_u32_e32 v3, 0x8000, v5
	v_perm_b32 v3, v3, v4, s81
	v_add_u32_e32 v4, 0x8000, v17
	v_add_u32_e32 v5, 0x8000, v16
	v_perm_b32 v4, v4, v5, s81
	v_add_u32_e32 v5, 0x8000, v6
	v_add_u32_e32 v6, 0x8000, v18
	v_perm_b32 v5, v5, v6, s81
	flat_store_dwordx4 v[0:1], v[2:5] offset:3072
	s_andn2_b64 exec, exec, s[12:13]
	s_cbranch_execnz .LBB0_1141
